# lean K-loops on all four GEMMs; ds_reads double as the M0 wait-state fillers (no nop/mov fillers), merged vmcnt+lgkmcnt waits
# speedup vs baseline: 1.0019x; 1.0010x over previous
.LBB0_265:
	ds_read_b128 v[154:157], v161
	ds_read_b128 v[164:167], v161 offset:1024
	ds_read_b128 v[168:171], v161 offset:2048
	ds_read_b128 v[172:175], v161 offset:3072
	ds_read_b128 v[176:179], v162
	ds_read_b128 v[180:183], v162 offset:1024
	ds_read_b128 v[184:187], v162 offset:2048
	ds_read_b128 v[188:191], v162 offset:3072
	ds_read_b128 v[192:195], v163
	ds_read_b128 v[196:199], v163 offset:1024
	ds_read_b128 v[200:203], v163 offset:2048
	ds_read_b128 v[204:207], v163 offset:3072
	ds_read_b128 v[208:211], v163 offset:4096
	ds_read_b128 v[212:215], v163 offset:5120
	s_add_i32 m0, s33, 0xc000
	ds_read_b128 v[216:219], v163 offset:6144
	global_load_lds_dwordx4 v146, s[72:73]
	s_add_i32 m0, s33, 0xe000
	ds_read_b128 v[220:223], v163 offset:7168
	global_load_lds_dwordx4 v148, s[72:73]
	s_waitcnt vmcnt(8) lgkmcnt(0)
	s_barrier
	s_setprio 1
	v_mfma_f32_16x16x32_bf16 v[126:129], v[154:157], v[192:195], v[126:129]
	v_mfma_f32_16x16x32_bf16 v[122:125], v[168:171], v[192:195], v[122:125]
	v_mfma_f32_16x16x32_bf16 v[110:113], v[154:157], v[200:203], v[110:113]
	s_add_u32 s12, s72, 0xfff00080
	v_mfma_f32_16x16x32_bf16 v[106:109], v[168:171], v[200:203], v[106:109]
	s_addc_u32 s13, s73, -1
	v_mfma_f32_16x16x32_bf16 v[94:97], v[154:157], v[208:211], v[94:97]
	s_cmp_eq_u32 s83, 60
	v_mfma_f32_16x16x32_bf16 v[90:93], v[168:171], v[208:211], v[90:93]
	s_cselect_b32 s77, s55, s13
	v_mfma_f32_16x16x32_bf16 v[78:81], v[154:157], v[216:219], v[78:81]
	s_cselect_b32 s76, s71, s12
	v_mfma_f32_16x16x32_bf16 v[74:77], v[168:171], v[216:219], v[74:77]
	s_cselect_b32 s75, s53, s82
	v_mfma_f32_16x16x32_bf16 v[126:129], v[164:167], v[196:199], v[126:129]
	s_cselect_b32 s74, s80, s81
	v_mfma_f32_16x16x32_bf16 v[122:125], v[172:175], v[196:199], v[122:125]
	s_add_u32 s98, s74, 0x100000
	v_mfma_f32_16x16x32_bf16 v[110:113], v[164:167], v[204:207], v[110:113]
	s_addc_u32 s99, s75, 0
	v_mfma_f32_16x16x32_bf16 v[106:109], v[172:175], v[204:207], v[106:109]
	s_add_u32 s100, s76, 0x100000
	v_mfma_f32_16x16x32_bf16 v[94:97], v[164:167], v[212:215], v[94:97]
	s_addc_u32 s101, s77, 0
	v_mfma_f32_16x16x32_bf16 v[90:93], v[172:175], v[212:215], v[90:93]
	v_mfma_f32_16x16x32_bf16 v[78:81], v[164:167], v[220:223], v[78:81]
	v_mfma_f32_16x16x32_bf16 v[74:77], v[172:175], v[220:223], v[74:77]
	v_mfma_f32_16x16x32_bf16 v[118:121], v[176:179], v[192:195], v[118:121]
	v_mfma_f32_16x16x32_bf16 v[114:117], v[184:187], v[192:195], v[114:117]
	v_mfma_f32_16x16x32_bf16 v[102:105], v[176:179], v[200:203], v[102:105]
	v_mfma_f32_16x16x32_bf16 v[98:101], v[184:187], v[200:203], v[98:101]
	v_mfma_f32_16x16x32_bf16 v[86:89], v[176:179], v[208:211], v[86:89]
	v_mfma_f32_16x16x32_bf16 v[82:85], v[184:187], v[208:211], v[82:85]
	v_mfma_f32_16x16x32_bf16 v[70:73], v[176:179], v[216:219], v[70:73]
	v_mfma_f32_16x16x32_bf16 v[66:69], v[184:187], v[216:219], v[66:69]
	v_mfma_f32_16x16x32_bf16 v[118:121], v[180:183], v[196:199], v[118:121]
	v_mfma_f32_16x16x32_bf16 v[114:117], v[188:191], v[196:199], v[114:117]
	v_mfma_f32_16x16x32_bf16 v[102:105], v[180:183], v[204:207], v[102:105]
	v_mfma_f32_16x16x32_bf16 v[98:101], v[188:191], v[204:207], v[98:101]
	v_mfma_f32_16x16x32_bf16 v[86:89], v[180:183], v[212:215], v[86:89]
	v_mfma_f32_16x16x32_bf16 v[82:85], v[188:191], v[212:215], v[82:85]
	v_mfma_f32_16x16x32_bf16 v[70:73], v[180:183], v[220:223], v[70:73]
	v_mfma_f32_16x16x32_bf16 v[66:69], v[188:191], v[220:223], v[66:69]
	s_setprio 0
	s_barrier
	ds_read_b128 v[192:195], v163 offset:16384
	ds_read_b128 v[196:199], v163 offset:17408
	s_add_i32 m0, s33, 0x10000
	ds_read_b128 v[200:203], v163 offset:18432
	global_load_lds_dwordx4 v134, s[74:75]
	s_add_i32 m0, s33, 0x12000
	ds_read_b128 v[204:207], v163 offset:19456
	global_load_lds_dwordx4 v130, s[74:75]
	s_add_i32 m0, s33, 0x14000
	ds_read_b128 v[208:211], v163 offset:20480
	global_load_lds_dwordx4 v134, s[98:99]
	s_add_i32 m0, s33, 0x16000
	ds_read_b128 v[212:215], v163 offset:21504
	global_load_lds_dwordx4 v130, s[98:99]
	s_mov_b32 m0, s33
	ds_read_b128 v[216:219], v163 offset:22528
	global_load_lds_dwordx4 v136, s[76:77]
	s_add_i32 m0, s33, 0x2000
	ds_read_b128 v[220:223], v163 offset:23552
	global_load_lds_dwordx4 v132, s[76:77]
	s_waitcnt vmcnt(8) lgkmcnt(0)
	s_barrier
	s_setprio 1
	v_mfma_f32_16x16x32_bf16 v[62:65], v[154:157], v[192:195], v[62:65]
	v_mfma_f32_16x16x32_bf16 v[58:61], v[168:171], v[192:195], v[58:61]
	v_mfma_f32_16x16x32_bf16 v[46:49], v[154:157], v[200:203], v[46:49]
	v_mfma_f32_16x16x32_bf16 v[42:45], v[168:171], v[200:203], v[42:45]
	v_mfma_f32_16x16x32_bf16 v[30:33], v[154:157], v[208:211], v[30:33]
	v_mfma_f32_16x16x32_bf16 v[26:29], v[168:171], v[208:211], v[26:29]
	v_mfma_f32_16x16x32_bf16 v[14:17], v[154:157], v[216:219], v[14:17]
	v_mfma_f32_16x16x32_bf16 v[10:13], v[168:171], v[216:219], v[10:13]
	v_mfma_f32_16x16x32_bf16 v[62:65], v[164:167], v[196:199], v[62:65]
	v_mfma_f32_16x16x32_bf16 v[58:61], v[172:175], v[196:199], v[58:61]
	v_mfma_f32_16x16x32_bf16 v[46:49], v[164:167], v[204:207], v[46:49]
	v_mfma_f32_16x16x32_bf16 v[42:45], v[172:175], v[204:207], v[42:45]
	v_mfma_f32_16x16x32_bf16 v[30:33], v[164:167], v[212:215], v[30:33]
	v_mfma_f32_16x16x32_bf16 v[26:29], v[172:175], v[212:215], v[26:29]
	v_mfma_f32_16x16x32_bf16 v[14:17], v[164:167], v[220:223], v[14:17]
	v_mfma_f32_16x16x32_bf16 v[10:13], v[172:175], v[220:223], v[10:13]
	v_mfma_f32_16x16x32_bf16 v[54:57], v[176:179], v[192:195], v[54:57]
	v_mfma_f32_16x16x32_bf16 v[50:53], v[184:187], v[192:195], v[50:53]
	v_mfma_f32_16x16x32_bf16 v[38:41], v[176:179], v[200:203], v[38:41]
	v_mfma_f32_16x16x32_bf16 v[34:37], v[184:187], v[200:203], v[34:37]
	v_mfma_f32_16x16x32_bf16 v[22:25], v[176:179], v[208:211], v[22:25]
	v_mfma_f32_16x16x32_bf16 v[18:21], v[184:187], v[208:211], v[18:21]
	v_mfma_f32_16x16x32_bf16 v[6:9], v[176:179], v[216:219], v[6:9]
	v_mfma_f32_16x16x32_bf16 v[2:5], v[184:187], v[216:219], v[2:5]
	v_mfma_f32_16x16x32_bf16 v[54:57], v[180:183], v[196:199], v[54:57]
	v_mfma_f32_16x16x32_bf16 v[50:53], v[188:191], v[196:199], v[50:53]
	v_mfma_f32_16x16x32_bf16 v[38:41], v[180:183], v[204:207], v[38:41]
	v_mfma_f32_16x16x32_bf16 v[34:37], v[188:191], v[204:207], v[34:37]
	v_mfma_f32_16x16x32_bf16 v[22:25], v[180:183], v[212:215], v[22:25]
	v_mfma_f32_16x16x32_bf16 v[18:21], v[188:191], v[212:215], v[18:21]
	v_mfma_f32_16x16x32_bf16 v[6:9], v[180:183], v[220:223], v[6:9]
	v_mfma_f32_16x16x32_bf16 v[2:5], v[188:191], v[220:223], v[2:5]
	s_setprio 0
	s_barrier
	ds_read_b128 v[154:157], v226
	ds_read_b128 v[164:167], v226 offset:1024
	ds_read_b128 v[168:171], v226 offset:2048
	ds_read_b128 v[172:175], v226 offset:3072
	ds_read_b128 v[176:179], v227
	ds_read_b128 v[180:183], v227 offset:1024
	ds_read_b128 v[184:187], v227 offset:2048
	ds_read_b128 v[188:191], v227 offset:3072
	ds_read_b128 v[192:195], v163 offset:32768
	ds_read_b128 v[196:199], v163 offset:33792
	ds_read_b128 v[200:203], v163 offset:34816
	ds_read_b128 v[204:207], v163 offset:35840
	ds_read_b128 v[208:211], v163 offset:36864
	ds_read_b128 v[212:215], v163 offset:37888
	s_add_i32 m0, s33, 0x4000
	ds_read_b128 v[216:219], v163 offset:38912
	global_load_lds_dwordx4 v136, s[100:101]
	s_add_i32 m0, s33, 0x6000
	ds_read_b128 v[220:223], v163 offset:39936
	global_load_lds_dwordx4 v132, s[100:101]
	s_waitcnt vmcnt(8) lgkmcnt(0)
	s_barrier
	s_setprio 1
	v_mfma_f32_16x16x32_bf16 v[126:129], v[154:157], v[192:195], v[126:129]
	v_mfma_f32_16x16x32_bf16 v[122:125], v[168:171], v[192:195], v[122:125]
	v_mfma_f32_16x16x32_bf16 v[110:113], v[154:157], v[200:203], v[110:113]
	v_mfma_f32_16x16x32_bf16 v[106:109], v[168:171], v[200:203], v[106:109]
	v_mfma_f32_16x16x32_bf16 v[94:97], v[154:157], v[208:211], v[94:97]
	v_mfma_f32_16x16x32_bf16 v[90:93], v[168:171], v[208:211], v[90:93]
	v_mfma_f32_16x16x32_bf16 v[78:81], v[154:157], v[216:219], v[78:81]
	v_mfma_f32_16x16x32_bf16 v[74:77], v[168:171], v[216:219], v[74:77]
	v_mfma_f32_16x16x32_bf16 v[126:129], v[164:167], v[196:199], v[126:129]
	v_mfma_f32_16x16x32_bf16 v[122:125], v[172:175], v[196:199], v[122:125]
	v_mfma_f32_16x16x32_bf16 v[110:113], v[164:167], v[204:207], v[110:113]
	v_mfma_f32_16x16x32_bf16 v[106:109], v[172:175], v[204:207], v[106:109]
	v_mfma_f32_16x16x32_bf16 v[94:97], v[164:167], v[212:215], v[94:97]
	v_mfma_f32_16x16x32_bf16 v[90:93], v[172:175], v[212:215], v[90:93]
	v_mfma_f32_16x16x32_bf16 v[78:81], v[164:167], v[220:223], v[78:81]
	v_mfma_f32_16x16x32_bf16 v[74:77], v[172:175], v[220:223], v[74:77]
	v_mfma_f32_16x16x32_bf16 v[118:121], v[176:179], v[192:195], v[118:121]
	v_mfma_f32_16x16x32_bf16 v[114:117], v[184:187], v[192:195], v[114:117]
	v_mfma_f32_16x16x32_bf16 v[102:105], v[176:179], v[200:203], v[102:105]
	v_mfma_f32_16x16x32_bf16 v[98:101], v[184:187], v[200:203], v[98:101]
	v_mfma_f32_16x16x32_bf16 v[86:89], v[176:179], v[208:211], v[86:89]
	v_mfma_f32_16x16x32_bf16 v[82:85], v[184:187], v[208:211], v[82:85]
	v_mfma_f32_16x16x32_bf16 v[70:73], v[176:179], v[216:219], v[70:73]
	v_mfma_f32_16x16x32_bf16 v[66:69], v[184:187], v[216:219], v[66:69]
	v_mfma_f32_16x16x32_bf16 v[118:121], v[180:183], v[196:199], v[118:121]
	v_mfma_f32_16x16x32_bf16 v[114:117], v[188:191], v[196:199], v[114:117]
	v_mfma_f32_16x16x32_bf16 v[102:105], v[180:183], v[204:207], v[102:105]
	v_mfma_f32_16x16x32_bf16 v[98:101], v[188:191], v[204:207], v[98:101]
	v_mfma_f32_16x16x32_bf16 v[86:89], v[180:183], v[212:215], v[86:89]
	v_mfma_f32_16x16x32_bf16 v[82:85], v[188:191], v[212:215], v[82:85]
	v_mfma_f32_16x16x32_bf16 v[70:73], v[180:183], v[220:223], v[70:73]
	v_mfma_f32_16x16x32_bf16 v[66:69], v[188:191], v[220:223], v[66:69]
	s_setprio 0
	s_barrier
	ds_read_b128 v[192:195], v163 offset:49152
	ds_read_b128 v[196:199], v163 offset:50176
	s_add_i32 m0, s33, 0x17f80
	ds_read_b128 v[200:203], v163 offset:51200
	global_load_lds_dwordx4 v134, s[74:75] offset:128
	s_add_i32 m0, s33, 0x19f80
	ds_read_b128 v[204:207], v163 offset:52224
	global_load_lds_dwordx4 v130, s[74:75] offset:128
	s_add_i32 m0, s33, 0x1bf80
	ds_read_b128 v[208:211], v163 offset:53248
	global_load_lds_dwordx4 v134, s[98:99] offset:128
	s_add_i32 m0, s33, 0x1df80
	ds_read_b128 v[212:215], v163 offset:54272
	global_load_lds_dwordx4 v130, s[98:99] offset:128
	s_add_i32 m0, s33, 0x7f80
	ds_read_b128 v[216:219], v163 offset:55296
	global_load_lds_dwordx4 v136, s[76:77] offset:128
	s_add_i32 m0, s33, 0x9f80
	ds_read_b128 v[220:223], v163 offset:56320
	global_load_lds_dwordx4 v132, s[76:77] offset:128
	s_waitcnt vmcnt(8) lgkmcnt(0)
	s_barrier
	s_setprio 1
	v_mfma_f32_16x16x32_bf16 v[62:65], v[154:157], v[192:195], v[62:65]
	v_mfma_f32_16x16x32_bf16 v[58:61], v[168:171], v[192:195], v[58:61]
	v_mfma_f32_16x16x32_bf16 v[46:49], v[154:157], v[200:203], v[46:49]
	v_mfma_f32_16x16x32_bf16 v[42:45], v[168:171], v[200:203], v[42:45]
	v_mfma_f32_16x16x32_bf16 v[30:33], v[154:157], v[208:211], v[30:33]
	v_mfma_f32_16x16x32_bf16 v[26:29], v[168:171], v[208:211], v[26:29]
	v_mfma_f32_16x16x32_bf16 v[14:17], v[154:157], v[216:219], v[14:17]
	v_mfma_f32_16x16x32_bf16 v[10:13], v[168:171], v[216:219], v[10:13]
	v_mfma_f32_16x16x32_bf16 v[62:65], v[164:167], v[196:199], v[62:65]
	v_mfma_f32_16x16x32_bf16 v[58:61], v[172:175], v[196:199], v[58:61]
	v_mfma_f32_16x16x32_bf16 v[46:49], v[164:167], v[204:207], v[46:49]
	v_mfma_f32_16x16x32_bf16 v[42:45], v[172:175], v[204:207], v[42:45]
	v_mfma_f32_16x16x32_bf16 v[30:33], v[164:167], v[212:215], v[30:33]
	v_mfma_f32_16x16x32_bf16 v[26:29], v[172:175], v[212:215], v[26:29]
	v_mfma_f32_16x16x32_bf16 v[14:17], v[164:167], v[220:223], v[14:17]
	v_mfma_f32_16x16x32_bf16 v[10:13], v[172:175], v[220:223], v[10:13]
	v_mfma_f32_16x16x32_bf16 v[54:57], v[176:179], v[192:195], v[54:57]
	v_mfma_f32_16x16x32_bf16 v[50:53], v[184:187], v[192:195], v[50:53]
	v_mfma_f32_16x16x32_bf16 v[38:41], v[176:179], v[200:203], v[38:41]
	v_mfma_f32_16x16x32_bf16 v[34:37], v[184:187], v[200:203], v[34:37]
	v_mfma_f32_16x16x32_bf16 v[22:25], v[176:179], v[208:211], v[22:25]
	v_mfma_f32_16x16x32_bf16 v[18:21], v[184:187], v[208:211], v[18:21]
	v_mfma_f32_16x16x32_bf16 v[6:9], v[176:179], v[216:219], v[6:9]
	v_mfma_f32_16x16x32_bf16 v[2:5], v[184:187], v[216:219], v[2:5]
	v_mfma_f32_16x16x32_bf16 v[54:57], v[180:183], v[196:199], v[54:57]
	v_mfma_f32_16x16x32_bf16 v[50:53], v[188:191], v[196:199], v[50:53]
	s_add_i32 s83, s83, 2
	v_mfma_f32_16x16x32_bf16 v[38:41], v[180:183], v[204:207], v[38:41]
	s_add_u32 s72, s72, 0x100
	v_mfma_f32_16x16x32_bf16 v[34:37], v[188:191], v[204:207], v[34:37]
	s_addc_u32 s73, s73, 0
	v_mfma_f32_16x16x32_bf16 v[22:25], v[180:183], v[212:215], v[22:25]
	s_add_u32 s81, s81, 0x100
	v_mfma_f32_16x16x32_bf16 v[18:21], v[188:191], v[212:215], v[18:21]
	s_addc_u32 s82, s82, 0
	v_mfma_f32_16x16x32_bf16 v[6:9], v[180:183], v[220:223], v[6:9]
	s_cmp_gt_u32 s83, 61
	v_mfma_f32_16x16x32_bf16 v[2:5], v[188:191], v[220:223], v[2:5]
	s_setprio 0
	s_barrier
	s_cbranch_scc0 .LBB0_265
	s_and_b64 vcc, exec, s[46:47]
	s_cbranch_vccz .LBB0_268
	s_barrier

.LBB0_510:
	ds_read_b128 v[146:149], v152
	ds_read_b128 v[156:159], v152 offset:1024
	ds_read_b128 v[160:163], v152 offset:2048
	ds_read_b128 v[164:167], v152 offset:3072
	ds_read_b128 v[168:171], v153
	ds_read_b128 v[172:175], v153 offset:1024
	ds_read_b128 v[176:179], v153 offset:2048
	ds_read_b128 v[180:183], v153 offset:3072
	ds_read_b128 v[184:187], v154
	ds_read_b128 v[188:191], v154 offset:1024
	ds_read_b128 v[192:195], v154 offset:2048
	ds_read_b128 v[196:199], v154 offset:3072
	ds_read_b128 v[206:209], v154 offset:4096
	ds_read_b128 v[210:213], v154 offset:5120
	s_add_i32 m0, s1, 0xc000
	ds_read_b128 v[214:217], v154 offset:6144
	global_load_lds_dwordx4 v138, s[52:53]
	s_add_i32 m0, s1, 0xe000
	ds_read_b128 v[218:221], v154 offset:7168
	global_load_lds_dwordx4 v140, s[52:53]
	s_waitcnt vmcnt(8) lgkmcnt(0)
	s_barrier
	s_setprio 1
	v_mfma_f32_16x16x32_bf16 v[126:129], v[146:149], v[184:187], v[126:129]
	v_mfma_f32_16x16x32_bf16 v[122:125], v[160:163], v[184:187], v[122:125]
	v_mfma_f32_16x16x32_bf16 v[110:113], v[146:149], v[192:195], v[110:113]
	s_add_u32 s34, s52, 0xfff00080
	v_mfma_f32_16x16x32_bf16 v[106:109], v[160:163], v[192:195], v[106:109]
	s_addc_u32 s36, s53, -1
	v_mfma_f32_16x16x32_bf16 v[94:97], v[146:149], v[206:209], v[94:97]
	s_cmp_eq_u32 s62, 60
	v_mfma_f32_16x16x32_bf16 v[90:93], v[160:163], v[206:209], v[90:93]
	s_cselect_b32 s67, s45, s36
	v_mfma_f32_16x16x32_bf16 v[78:81], v[146:149], v[214:217], v[78:81]
	s_cselect_b32 s66, s51, s34
	v_mfma_f32_16x16x32_bf16 v[74:77], v[160:163], v[214:217], v[74:77]
	s_cselect_b32 s55, s23, s61
	v_mfma_f32_16x16x32_bf16 v[126:129], v[156:159], v[188:191], v[126:129]
	s_cselect_b32 s54, s59, s60
	v_mfma_f32_16x16x32_bf16 v[122:125], v[164:167], v[188:191], v[122:125]
	s_add_u32 s98, s54, 0x100000
	v_mfma_f32_16x16x32_bf16 v[110:113], v[156:159], v[196:199], v[110:113]
	s_addc_u32 s99, s55, 0
	v_mfma_f32_16x16x32_bf16 v[106:109], v[164:167], v[196:199], v[106:109]
	s_add_u32 s100, s66, 0x100000
	v_mfma_f32_16x16x32_bf16 v[94:97], v[156:159], v[210:213], v[94:97]
	s_addc_u32 s101, s67, 0
	v_mfma_f32_16x16x32_bf16 v[90:93], v[164:167], v[210:213], v[90:93]
	v_mfma_f32_16x16x32_bf16 v[78:81], v[156:159], v[218:221], v[78:81]
	v_mfma_f32_16x16x32_bf16 v[74:77], v[164:167], v[218:221], v[74:77]
	v_mfma_f32_16x16x32_bf16 v[118:121], v[168:171], v[184:187], v[118:121]
	v_mfma_f32_16x16x32_bf16 v[114:117], v[176:179], v[184:187], v[114:117]
	v_mfma_f32_16x16x32_bf16 v[102:105], v[168:171], v[192:195], v[102:105]
	v_mfma_f32_16x16x32_bf16 v[98:101], v[176:179], v[192:195], v[98:101]
	v_mfma_f32_16x16x32_bf16 v[86:89], v[168:171], v[206:209], v[86:89]
	v_mfma_f32_16x16x32_bf16 v[82:85], v[176:179], v[206:209], v[82:85]
	v_mfma_f32_16x16x32_bf16 v[70:73], v[168:171], v[214:217], v[70:73]
	v_mfma_f32_16x16x32_bf16 v[66:69], v[176:179], v[214:217], v[66:69]
	v_mfma_f32_16x16x32_bf16 v[118:121], v[172:175], v[188:191], v[118:121]
	v_mfma_f32_16x16x32_bf16 v[114:117], v[180:183], v[188:191], v[114:117]
	v_mfma_f32_16x16x32_bf16 v[102:105], v[172:175], v[196:199], v[102:105]
	v_mfma_f32_16x16x32_bf16 v[98:101], v[180:183], v[196:199], v[98:101]
	v_mfma_f32_16x16x32_bf16 v[86:89], v[172:175], v[210:213], v[86:89]
	v_mfma_f32_16x16x32_bf16 v[82:85], v[180:183], v[210:213], v[82:85]
	v_mfma_f32_16x16x32_bf16 v[70:73], v[172:175], v[218:221], v[70:73]
	v_mfma_f32_16x16x32_bf16 v[66:69], v[180:183], v[218:221], v[66:69]
	s_setprio 0
	s_barrier
	ds_read_b128 v[184:187], v154 offset:16384
	ds_read_b128 v[188:191], v154 offset:17408
	s_add_i32 m0, s1, 0x10000
	ds_read_b128 v[192:195], v154 offset:18432
	global_load_lds_dwordx4 v132, s[54:55]
	s_add_i32 m0, s1, 0x12000
	ds_read_b128 v[196:199], v154 offset:19456
	global_load_lds_dwordx4 v136, s[54:55]
	s_add_i32 m0, s1, 0x14000
	ds_read_b128 v[206:209], v154 offset:20480
	global_load_lds_dwordx4 v132, s[98:99]
	s_add_i32 m0, s1, 0x16000
	ds_read_b128 v[210:213], v154 offset:21504
	global_load_lds_dwordx4 v136, s[98:99]
	s_mov_b32 m0, s1
	ds_read_b128 v[214:217], v154 offset:22528
	global_load_lds_dwordx4 v130, s[66:67]
	s_add_i32 m0, s1, 0x2000
	ds_read_b128 v[218:221], v154 offset:23552
	global_load_lds_dwordx4 v134, s[66:67]
	s_waitcnt vmcnt(8) lgkmcnt(0)
	s_barrier
	s_setprio 1
	v_mfma_f32_16x16x32_bf16 v[62:65], v[146:149], v[184:187], v[62:65]
	v_mfma_f32_16x16x32_bf16 v[58:61], v[160:163], v[184:187], v[58:61]
	v_mfma_f32_16x16x32_bf16 v[46:49], v[146:149], v[192:195], v[46:49]
	v_mfma_f32_16x16x32_bf16 v[42:45], v[160:163], v[192:195], v[42:45]
	v_mfma_f32_16x16x32_bf16 v[30:33], v[146:149], v[206:209], v[30:33]
	v_mfma_f32_16x16x32_bf16 v[26:29], v[160:163], v[206:209], v[26:29]
	v_mfma_f32_16x16x32_bf16 v[14:17], v[146:149], v[214:217], v[14:17]
	v_mfma_f32_16x16x32_bf16 v[10:13], v[160:163], v[214:217], v[10:13]
	v_mfma_f32_16x16x32_bf16 v[62:65], v[156:159], v[188:191], v[62:65]
	v_mfma_f32_16x16x32_bf16 v[58:61], v[164:167], v[188:191], v[58:61]
	v_mfma_f32_16x16x32_bf16 v[46:49], v[156:159], v[196:199], v[46:49]
	v_mfma_f32_16x16x32_bf16 v[42:45], v[164:167], v[196:199], v[42:45]
	v_mfma_f32_16x16x32_bf16 v[30:33], v[156:159], v[210:213], v[30:33]
	v_mfma_f32_16x16x32_bf16 v[26:29], v[164:167], v[210:213], v[26:29]
	v_mfma_f32_16x16x32_bf16 v[14:17], v[156:159], v[218:221], v[14:17]
	v_mfma_f32_16x16x32_bf16 v[10:13], v[164:167], v[218:221], v[10:13]
	v_mfma_f32_16x16x32_bf16 v[54:57], v[168:171], v[184:187], v[54:57]
	v_mfma_f32_16x16x32_bf16 v[50:53], v[176:179], v[184:187], v[50:53]
	v_mfma_f32_16x16x32_bf16 v[38:41], v[168:171], v[192:195], v[38:41]
	v_mfma_f32_16x16x32_bf16 v[34:37], v[176:179], v[192:195], v[34:37]
	v_mfma_f32_16x16x32_bf16 v[22:25], v[168:171], v[206:209], v[22:25]
	v_mfma_f32_16x16x32_bf16 v[18:21], v[176:179], v[206:209], v[18:21]
	v_mfma_f32_16x16x32_bf16 v[6:9], v[168:171], v[214:217], v[6:9]
	v_mfma_f32_16x16x32_bf16 v[2:5], v[176:179], v[214:217], v[2:5]
	v_mfma_f32_16x16x32_bf16 v[54:57], v[172:175], v[188:191], v[54:57]
	v_mfma_f32_16x16x32_bf16 v[50:53], v[180:183], v[188:191], v[50:53]
	v_mfma_f32_16x16x32_bf16 v[38:41], v[172:175], v[196:199], v[38:41]
	v_mfma_f32_16x16x32_bf16 v[34:37], v[180:183], v[196:199], v[34:37]
	v_mfma_f32_16x16x32_bf16 v[22:25], v[172:175], v[210:213], v[22:25]
	v_mfma_f32_16x16x32_bf16 v[18:21], v[180:183], v[210:213], v[18:21]
	v_mfma_f32_16x16x32_bf16 v[6:9], v[172:175], v[218:221], v[6:9]
	v_mfma_f32_16x16x32_bf16 v[2:5], v[180:183], v[218:221], v[2:5]
	s_setprio 0
	s_barrier
	ds_read_b128 v[146:149], v226
	ds_read_b128 v[156:159], v226 offset:1024
	ds_read_b128 v[160:163], v226 offset:2048
	ds_read_b128 v[164:167], v226 offset:3072
	ds_read_b128 v[168:171], v227
	ds_read_b128 v[172:175], v227 offset:1024
	ds_read_b128 v[176:179], v227 offset:2048
	ds_read_b128 v[180:183], v227 offset:3072
	ds_read_b128 v[184:187], v154 offset:32768
	ds_read_b128 v[188:191], v154 offset:33792
	ds_read_b128 v[192:195], v154 offset:34816
	ds_read_b128 v[196:199], v154 offset:35840
	ds_read_b128 v[206:209], v154 offset:36864
	ds_read_b128 v[210:213], v154 offset:37888
	s_add_i32 m0, s1, 0x4000
	ds_read_b128 v[214:217], v154 offset:38912
	global_load_lds_dwordx4 v130, s[100:101]
	s_add_i32 m0, s1, 0x6000
	ds_read_b128 v[218:221], v154 offset:39936
	global_load_lds_dwordx4 v134, s[100:101]
	s_waitcnt vmcnt(8) lgkmcnt(0)
	s_barrier
	s_setprio 1
	v_mfma_f32_16x16x32_bf16 v[126:129], v[146:149], v[184:187], v[126:129]
	v_mfma_f32_16x16x32_bf16 v[122:125], v[160:163], v[184:187], v[122:125]
	v_mfma_f32_16x16x32_bf16 v[110:113], v[146:149], v[192:195], v[110:113]
	v_mfma_f32_16x16x32_bf16 v[106:109], v[160:163], v[192:195], v[106:109]
	v_mfma_f32_16x16x32_bf16 v[94:97], v[146:149], v[206:209], v[94:97]
	v_mfma_f32_16x16x32_bf16 v[90:93], v[160:163], v[206:209], v[90:93]
	v_mfma_f32_16x16x32_bf16 v[78:81], v[146:149], v[214:217], v[78:81]
	v_mfma_f32_16x16x32_bf16 v[74:77], v[160:163], v[214:217], v[74:77]
	v_mfma_f32_16x16x32_bf16 v[126:129], v[156:159], v[188:191], v[126:129]
	v_mfma_f32_16x16x32_bf16 v[122:125], v[164:167], v[188:191], v[122:125]
	v_mfma_f32_16x16x32_bf16 v[110:113], v[156:159], v[196:199], v[110:113]
	v_mfma_f32_16x16x32_bf16 v[106:109], v[164:167], v[196:199], v[106:109]
	v_mfma_f32_16x16x32_bf16 v[94:97], v[156:159], v[210:213], v[94:97]
	v_mfma_f32_16x16x32_bf16 v[90:93], v[164:167], v[210:213], v[90:93]
	v_mfma_f32_16x16x32_bf16 v[78:81], v[156:159], v[218:221], v[78:81]
	v_mfma_f32_16x16x32_bf16 v[74:77], v[164:167], v[218:221], v[74:77]
	v_mfma_f32_16x16x32_bf16 v[118:121], v[168:171], v[184:187], v[118:121]
	v_mfma_f32_16x16x32_bf16 v[114:117], v[176:179], v[184:187], v[114:117]
	v_mfma_f32_16x16x32_bf16 v[102:105], v[168:171], v[192:195], v[102:105]
	v_mfma_f32_16x16x32_bf16 v[98:101], v[176:179], v[192:195], v[98:101]
	v_mfma_f32_16x16x32_bf16 v[86:89], v[168:171], v[206:209], v[86:89]
	v_mfma_f32_16x16x32_bf16 v[82:85], v[176:179], v[206:209], v[82:85]
	v_mfma_f32_16x16x32_bf16 v[70:73], v[168:171], v[214:217], v[70:73]
	v_mfma_f32_16x16x32_bf16 v[66:69], v[176:179], v[214:217], v[66:69]
	v_mfma_f32_16x16x32_bf16 v[118:121], v[172:175], v[188:191], v[118:121]
	v_mfma_f32_16x16x32_bf16 v[114:117], v[180:183], v[188:191], v[114:117]
	v_mfma_f32_16x16x32_bf16 v[102:105], v[172:175], v[196:199], v[102:105]
	v_mfma_f32_16x16x32_bf16 v[98:101], v[180:183], v[196:199], v[98:101]
	v_mfma_f32_16x16x32_bf16 v[86:89], v[172:175], v[210:213], v[86:89]
	v_mfma_f32_16x16x32_bf16 v[82:85], v[180:183], v[210:213], v[82:85]
	v_mfma_f32_16x16x32_bf16 v[70:73], v[172:175], v[218:221], v[70:73]
	v_mfma_f32_16x16x32_bf16 v[66:69], v[180:183], v[218:221], v[66:69]
	s_setprio 0
	s_barrier
	ds_read_b128 v[184:187], v154 offset:49152
	ds_read_b128 v[188:191], v154 offset:50176
	s_add_i32 m0, s1, 0x17f80
	ds_read_b128 v[192:195], v154 offset:51200
	global_load_lds_dwordx4 v132, s[54:55] offset:128
	s_add_i32 m0, s1, 0x19f80
	ds_read_b128 v[196:199], v154 offset:52224
	global_load_lds_dwordx4 v136, s[54:55] offset:128
	s_add_i32 m0, s1, 0x1bf80
	ds_read_b128 v[206:209], v154 offset:53248
	global_load_lds_dwordx4 v132, s[98:99] offset:128
	s_add_i32 m0, s1, 0x1df80
	ds_read_b128 v[210:213], v154 offset:54272
	global_load_lds_dwordx4 v136, s[98:99] offset:128
	s_add_i32 m0, s1, 0x7f80
	ds_read_b128 v[214:217], v154 offset:55296
	global_load_lds_dwordx4 v130, s[66:67] offset:128
	s_add_i32 m0, s1, 0x9f80
	ds_read_b128 v[218:221], v154 offset:56320
	global_load_lds_dwordx4 v134, s[66:67] offset:128
	s_waitcnt vmcnt(8) lgkmcnt(0)
	s_barrier
	s_setprio 1
	v_mfma_f32_16x16x32_bf16 v[62:65], v[146:149], v[184:187], v[62:65]
	v_mfma_f32_16x16x32_bf16 v[58:61], v[160:163], v[184:187], v[58:61]
	v_mfma_f32_16x16x32_bf16 v[46:49], v[146:149], v[192:195], v[46:49]
	v_mfma_f32_16x16x32_bf16 v[42:45], v[160:163], v[192:195], v[42:45]
	v_mfma_f32_16x16x32_bf16 v[30:33], v[146:149], v[206:209], v[30:33]
	v_mfma_f32_16x16x32_bf16 v[26:29], v[160:163], v[206:209], v[26:29]
	v_mfma_f32_16x16x32_bf16 v[14:17], v[146:149], v[214:217], v[14:17]
	v_mfma_f32_16x16x32_bf16 v[10:13], v[160:163], v[214:217], v[10:13]
	v_mfma_f32_16x16x32_bf16 v[62:65], v[156:159], v[188:191], v[62:65]
	v_mfma_f32_16x16x32_bf16 v[58:61], v[164:167], v[188:191], v[58:61]
	v_mfma_f32_16x16x32_bf16 v[46:49], v[156:159], v[196:199], v[46:49]
	v_mfma_f32_16x16x32_bf16 v[42:45], v[164:167], v[196:199], v[42:45]
	v_mfma_f32_16x16x32_bf16 v[30:33], v[156:159], v[210:213], v[30:33]
	v_mfma_f32_16x16x32_bf16 v[26:29], v[164:167], v[210:213], v[26:29]
	v_mfma_f32_16x16x32_bf16 v[14:17], v[156:159], v[218:221], v[14:17]
	v_mfma_f32_16x16x32_bf16 v[10:13], v[164:167], v[218:221], v[10:13]
	v_mfma_f32_16x16x32_bf16 v[54:57], v[168:171], v[184:187], v[54:57]
	v_mfma_f32_16x16x32_bf16 v[50:53], v[176:179], v[184:187], v[50:53]
	v_mfma_f32_16x16x32_bf16 v[38:41], v[168:171], v[192:195], v[38:41]
	v_mfma_f32_16x16x32_bf16 v[34:37], v[176:179], v[192:195], v[34:37]
	v_mfma_f32_16x16x32_bf16 v[22:25], v[168:171], v[206:209], v[22:25]
	v_mfma_f32_16x16x32_bf16 v[18:21], v[176:179], v[206:209], v[18:21]
	v_mfma_f32_16x16x32_bf16 v[6:9], v[168:171], v[214:217], v[6:9]
	v_mfma_f32_16x16x32_bf16 v[2:5], v[176:179], v[214:217], v[2:5]
	v_mfma_f32_16x16x32_bf16 v[54:57], v[172:175], v[188:191], v[54:57]
	v_mfma_f32_16x16x32_bf16 v[50:53], v[180:183], v[188:191], v[50:53]
	s_add_i32 s62, s62, 2
	v_mfma_f32_16x16x32_bf16 v[38:41], v[172:175], v[196:199], v[38:41]
	s_add_u32 s60, s60, 0x100
	v_mfma_f32_16x16x32_bf16 v[34:37], v[180:183], v[196:199], v[34:37]
	s_addc_u32 s61, s61, 0
	v_mfma_f32_16x16x32_bf16 v[22:25], v[172:175], v[210:213], v[22:25]
	s_add_u32 s52, s52, 0x100
	v_mfma_f32_16x16x32_bf16 v[18:21], v[180:183], v[210:213], v[18:21]
	s_addc_u32 s53, s53, 0
	v_mfma_f32_16x16x32_bf16 v[6:9], v[172:175], v[218:221], v[6:9]
	s_cmp_gt_u32 s62, 61
	v_mfma_f32_16x16x32_bf16 v[2:5], v[180:183], v[218:221], v[2:5]
	s_setprio 0
	s_barrier
	s_cbranch_scc0 .LBB0_510
	s_and_b64 vcc, exec, s[20:21]
	s_cbranch_vccz .LBB0_513
	s_barrier

.LBB0_651:
	ds_read_b128 v[130:133], v210
	ds_read_b128 v[134:137], v210 offset:1024
	ds_read_b128 v[138:141], v210 offset:2048
	ds_read_b128 v[142:145], v210 offset:3072
	ds_read_b128 v[146:149], v211
	ds_read_b128 v[150:153], v211 offset:1024
	ds_read_b128 v[154:157], v211 offset:2048
	ds_read_b128 v[158:161], v211 offset:3072
	ds_read_b128 v[162:165], v212
	ds_read_b128 v[166:169], v212 offset:1024
	ds_read_b128 v[188:191], v212 offset:2048
	ds_read_b128 v[192:195], v212 offset:3072
	ds_read_b128 v[196:199], v212 offset:4096
	ds_read_b128 v[214:217], v212 offset:5120
	s_add_i32 m0, s39, 0xc000
	ds_read_b128 v[218:221], v212 offset:6144
	global_load_lds_dwordx4 v180, s[88:89]
	s_add_i32 m0, s39, 0xe000
	ds_read_b128 v[222:225], v212 offset:7168
	global_load_lds_dwordx4 v182, s[88:89]
	s_waitcnt vmcnt(8) lgkmcnt(0)
	s_barrier
	s_setprio 1
	v_mfma_f32_16x16x32_bf16 v[126:129], v[130:133], v[162:165], v[126:129]
	v_mfma_f32_16x16x32_bf16 v[62:65], v[138:141], v[162:165], v[62:65]
	v_mfma_f32_16x16x32_bf16 v[122:125], v[130:133], v[188:191], v[122:125]
	s_add_u32 s90, s88, 0x100
	v_mfma_f32_16x16x32_bf16 v[58:61], v[138:141], v[188:191], v[58:61]
	s_addc_u32 s91, s89, 0
	v_mfma_f32_16x16x32_bf16 v[110:113], v[130:133], v[196:199], v[110:113]
	s_cmp_eq_u32 s66, 60
	v_mfma_f32_16x16x32_bf16 v[50:53], v[138:141], v[196:199], v[50:53]
	s_cselect_b32 s95, s79, s91
	v_mfma_f32_16x16x32_bf16 v[106:109], v[130:133], v[218:221], v[106:109]
	s_cselect_b32 s94, s85, s90
	v_mfma_f32_16x16x32_bf16 v[42:45], v[138:141], v[218:221], v[42:45]
	s_cselect_b32 s93, s77, vcc_hi
	v_mfma_f32_16x16x32_bf16 v[126:129], v[134:137], v[166:169], v[126:129]
	s_cselect_b32 s92, s87, vcc_lo
	v_mfma_f32_16x16x32_bf16 v[62:65], v[142:145], v[166:169], v[62:65]
	s_add_u32 s98, s92, 0x100000
	v_mfma_f32_16x16x32_bf16 v[122:125], v[134:137], v[192:195], v[122:125]
	s_addc_u32 s99, s93, 0
	v_mfma_f32_16x16x32_bf16 v[58:61], v[142:145], v[192:195], v[58:61]
	s_add_u32 s100, s94, 0x100000
	v_mfma_f32_16x16x32_bf16 v[110:113], v[134:137], v[214:217], v[110:113]
	s_addc_u32 s101, s95, 0
	v_mfma_f32_16x16x32_bf16 v[50:53], v[142:145], v[214:217], v[50:53]
	v_mfma_f32_16x16x32_bf16 v[106:109], v[134:137], v[222:225], v[106:109]
	v_mfma_f32_16x16x32_bf16 v[42:45], v[142:145], v[222:225], v[42:45]
	v_mfma_f32_16x16x32_bf16 v[118:121], v[146:149], v[162:165], v[118:121]
	v_mfma_f32_16x16x32_bf16 v[54:57], v[154:157], v[162:165], v[54:57]
	v_mfma_f32_16x16x32_bf16 v[114:117], v[146:149], v[188:191], v[114:117]
	v_mfma_f32_16x16x32_bf16 v[46:49], v[154:157], v[188:191], v[46:49]
	v_mfma_f32_16x16x32_bf16 v[102:105], v[146:149], v[196:199], v[102:105]
	v_mfma_f32_16x16x32_bf16 v[38:41], v[154:157], v[196:199], v[38:41]
	v_mfma_f32_16x16x32_bf16 v[98:101], v[146:149], v[218:221], v[98:101]
	v_mfma_f32_16x16x32_bf16 v[34:37], v[154:157], v[218:221], v[34:37]
	v_mfma_f32_16x16x32_bf16 v[118:121], v[150:153], v[166:169], v[118:121]
	v_mfma_f32_16x16x32_bf16 v[54:57], v[158:161], v[166:169], v[54:57]
	v_mfma_f32_16x16x32_bf16 v[114:117], v[150:153], v[192:195], v[114:117]
	v_mfma_f32_16x16x32_bf16 v[46:49], v[158:161], v[192:195], v[46:49]
	v_mfma_f32_16x16x32_bf16 v[102:105], v[150:153], v[214:217], v[102:105]
	v_mfma_f32_16x16x32_bf16 v[38:41], v[158:161], v[214:217], v[38:41]
	v_mfma_f32_16x16x32_bf16 v[98:101], v[150:153], v[222:225], v[98:101]
	v_mfma_f32_16x16x32_bf16 v[34:37], v[158:161], v[222:225], v[34:37]
	s_setprio 0
	s_barrier
	ds_read_b128 v[162:165], v212 offset:16384
	ds_read_b128 v[166:169], v212 offset:17408
	s_add_i32 m0, s39, 0x10000
	ds_read_b128 v[188:191], v212 offset:18432
	global_load_lds_dwordx4 v172, s[92:93]
	s_add_i32 m0, s39, 0x12000
	ds_read_b128 v[192:195], v212 offset:19456
	global_load_lds_dwordx4 v176, s[92:93]
	s_add_i32 m0, s39, 0x14000
	ds_read_b128 v[196:199], v212 offset:20480
	global_load_lds_dwordx4 v172, s[98:99]
	s_add_i32 m0, s39, 0x16000
	ds_read_b128 v[214:217], v212 offset:21504
	global_load_lds_dwordx4 v176, s[98:99]
	s_mov_b32 m0, s39
	ds_read_b128 v[218:221], v212 offset:22528
	global_load_lds_dwordx4 v170, s[94:95]
	s_add_i32 m0, s39, 0x2000
	ds_read_b128 v[222:225], v212 offset:23552
	global_load_lds_dwordx4 v174, s[94:95]
	s_waitcnt vmcnt(8) lgkmcnt(0)
	s_barrier
	s_setprio 1
	v_mfma_f32_16x16x32_bf16 v[94:97], v[130:133], v[162:165], v[94:97]
	v_mfma_f32_16x16x32_bf16 v[30:33], v[138:141], v[162:165], v[30:33]
	v_mfma_f32_16x16x32_bf16 v[90:93], v[130:133], v[188:191], v[90:93]
	v_mfma_f32_16x16x32_bf16 v[26:29], v[138:141], v[188:191], v[26:29]
	v_mfma_f32_16x16x32_bf16 v[82:85], v[130:133], v[196:199], v[82:85]
	v_mfma_f32_16x16x32_bf16 v[18:21], v[138:141], v[196:199], v[18:21]
	v_mfma_f32_16x16x32_bf16 v[74:77], v[130:133], v[218:221], v[74:77]
	v_mfma_f32_16x16x32_bf16 v[10:13], v[138:141], v[218:221], v[10:13]
	v_mfma_f32_16x16x32_bf16 v[94:97], v[134:137], v[166:169], v[94:97]
	v_mfma_f32_16x16x32_bf16 v[30:33], v[142:145], v[166:169], v[30:33]
	v_mfma_f32_16x16x32_bf16 v[90:93], v[134:137], v[192:195], v[90:93]
	v_mfma_f32_16x16x32_bf16 v[26:29], v[142:145], v[192:195], v[26:29]
	v_mfma_f32_16x16x32_bf16 v[82:85], v[134:137], v[214:217], v[82:85]
	v_mfma_f32_16x16x32_bf16 v[18:21], v[142:145], v[214:217], v[18:21]
	v_mfma_f32_16x16x32_bf16 v[74:77], v[134:137], v[222:225], v[74:77]
	v_mfma_f32_16x16x32_bf16 v[10:13], v[142:145], v[222:225], v[10:13]
	v_mfma_f32_16x16x32_bf16 v[86:89], v[146:149], v[162:165], v[86:89]
	v_mfma_f32_16x16x32_bf16 v[22:25], v[154:157], v[162:165], v[22:25]
	v_mfma_f32_16x16x32_bf16 v[78:81], v[146:149], v[188:191], v[78:81]
	v_mfma_f32_16x16x32_bf16 v[14:17], v[154:157], v[188:191], v[14:17]
	v_mfma_f32_16x16x32_bf16 v[70:73], v[146:149], v[196:199], v[70:73]
	v_mfma_f32_16x16x32_bf16 v[6:9], v[154:157], v[196:199], v[6:9]
	v_mfma_f32_16x16x32_bf16 v[66:69], v[146:149], v[218:221], v[66:69]
	v_mfma_f32_16x16x32_bf16 v[2:5], v[154:157], v[218:221], v[2:5]
	v_mfma_f32_16x16x32_bf16 v[86:89], v[150:153], v[166:169], v[86:89]
	v_mfma_f32_16x16x32_bf16 v[22:25], v[158:161], v[166:169], v[22:25]
	v_mfma_f32_16x16x32_bf16 v[78:81], v[150:153], v[192:195], v[78:81]
	v_mfma_f32_16x16x32_bf16 v[14:17], v[158:161], v[192:195], v[14:17]
	v_mfma_f32_16x16x32_bf16 v[70:73], v[150:153], v[214:217], v[70:73]
	v_mfma_f32_16x16x32_bf16 v[6:9], v[158:161], v[214:217], v[6:9]
	v_mfma_f32_16x16x32_bf16 v[66:69], v[150:153], v[222:225], v[66:69]
	v_mfma_f32_16x16x32_bf16 v[2:5], v[158:161], v[222:225], v[2:5]
	s_setprio 0
	s_barrier
	ds_read_b128 v[130:133], v226
	ds_read_b128 v[134:137], v226 offset:1024
	ds_read_b128 v[138:141], v226 offset:2048
	ds_read_b128 v[142:145], v226 offset:3072
	ds_read_b128 v[146:149], v227
	ds_read_b128 v[150:153], v227 offset:1024
	ds_read_b128 v[154:157], v227 offset:2048
	ds_read_b128 v[158:161], v227 offset:3072
	ds_read_b128 v[162:165], v212 offset:32768
	ds_read_b128 v[166:169], v212 offset:33792
	ds_read_b128 v[188:191], v212 offset:34816
	ds_read_b128 v[192:195], v212 offset:35840
	ds_read_b128 v[196:199], v212 offset:36864
	ds_read_b128 v[214:217], v212 offset:37888
	s_add_i32 m0, s39, 0x4000
	ds_read_b128 v[218:221], v212 offset:38912
	global_load_lds_dwordx4 v170, s[100:101]
	s_add_i32 m0, s39, 0x6000
	ds_read_b128 v[222:225], v212 offset:39936
	global_load_lds_dwordx4 v174, s[100:101]
	s_waitcnt vmcnt(8) lgkmcnt(0)
	s_barrier
	s_setprio 1
	v_mfma_f32_16x16x32_bf16 v[126:129], v[130:133], v[162:165], v[126:129]
	v_mfma_f32_16x16x32_bf16 v[62:65], v[138:141], v[162:165], v[62:65]
	v_mfma_f32_16x16x32_bf16 v[122:125], v[130:133], v[188:191], v[122:125]
	v_mfma_f32_16x16x32_bf16 v[58:61], v[138:141], v[188:191], v[58:61]
	v_mfma_f32_16x16x32_bf16 v[110:113], v[130:133], v[196:199], v[110:113]
	v_mfma_f32_16x16x32_bf16 v[50:53], v[138:141], v[196:199], v[50:53]
	v_mfma_f32_16x16x32_bf16 v[106:109], v[130:133], v[218:221], v[106:109]
	v_mfma_f32_16x16x32_bf16 v[42:45], v[138:141], v[218:221], v[42:45]
	v_mfma_f32_16x16x32_bf16 v[126:129], v[134:137], v[166:169], v[126:129]
	v_mfma_f32_16x16x32_bf16 v[62:65], v[142:145], v[166:169], v[62:65]
	v_mfma_f32_16x16x32_bf16 v[122:125], v[134:137], v[192:195], v[122:125]
	v_mfma_f32_16x16x32_bf16 v[58:61], v[142:145], v[192:195], v[58:61]
	v_mfma_f32_16x16x32_bf16 v[110:113], v[134:137], v[214:217], v[110:113]
	v_mfma_f32_16x16x32_bf16 v[50:53], v[142:145], v[214:217], v[50:53]
	v_mfma_f32_16x16x32_bf16 v[106:109], v[134:137], v[222:225], v[106:109]
	v_mfma_f32_16x16x32_bf16 v[42:45], v[142:145], v[222:225], v[42:45]
	v_mfma_f32_16x16x32_bf16 v[118:121], v[146:149], v[162:165], v[118:121]
	v_mfma_f32_16x16x32_bf16 v[54:57], v[154:157], v[162:165], v[54:57]
	v_mfma_f32_16x16x32_bf16 v[114:117], v[146:149], v[188:191], v[114:117]
	v_mfma_f32_16x16x32_bf16 v[46:49], v[154:157], v[188:191], v[46:49]
	v_mfma_f32_16x16x32_bf16 v[102:105], v[146:149], v[196:199], v[102:105]
	v_mfma_f32_16x16x32_bf16 v[38:41], v[154:157], v[196:199], v[38:41]
	v_mfma_f32_16x16x32_bf16 v[98:101], v[146:149], v[218:221], v[98:101]
	v_mfma_f32_16x16x32_bf16 v[34:37], v[154:157], v[218:221], v[34:37]
	v_mfma_f32_16x16x32_bf16 v[118:121], v[150:153], v[166:169], v[118:121]
	v_mfma_f32_16x16x32_bf16 v[54:57], v[158:161], v[166:169], v[54:57]
	v_mfma_f32_16x16x32_bf16 v[114:117], v[150:153], v[192:195], v[114:117]
	v_mfma_f32_16x16x32_bf16 v[46:49], v[158:161], v[192:195], v[46:49]
	v_mfma_f32_16x16x32_bf16 v[102:105], v[150:153], v[214:217], v[102:105]
	v_mfma_f32_16x16x32_bf16 v[38:41], v[158:161], v[214:217], v[38:41]
	v_mfma_f32_16x16x32_bf16 v[98:101], v[150:153], v[222:225], v[98:101]
	v_mfma_f32_16x16x32_bf16 v[34:37], v[158:161], v[222:225], v[34:37]
	s_setprio 0
	s_barrier
	ds_read_b128 v[162:165], v212 offset:49152
	ds_read_b128 v[166:169], v212 offset:50176
	s_add_i32 m0, s39, 0x17f80
	ds_read_b128 v[188:191], v212 offset:51200
	global_load_lds_dwordx4 v172, s[92:93] offset:128
	s_add_i32 m0, s39, 0x19f80
	ds_read_b128 v[192:195], v212 offset:52224
	global_load_lds_dwordx4 v176, s[92:93] offset:128
	s_add_i32 m0, s39, 0x1bf80
	ds_read_b128 v[196:199], v212 offset:53248
	global_load_lds_dwordx4 v172, s[98:99] offset:128
	s_add_i32 m0, s39, 0x1df80
	ds_read_b128 v[214:217], v212 offset:54272
	global_load_lds_dwordx4 v176, s[98:99] offset:128
	s_add_i32 m0, s39, 0x7f80
	ds_read_b128 v[218:221], v212 offset:55296
	global_load_lds_dwordx4 v170, s[94:95] offset:128
	s_add_i32 m0, s39, 0x9f80
	ds_read_b128 v[222:225], v212 offset:56320
	global_load_lds_dwordx4 v174, s[94:95] offset:128
	s_waitcnt vmcnt(8) lgkmcnt(0)
	s_barrier
	s_setprio 1
	v_mfma_f32_16x16x32_bf16 v[94:97], v[130:133], v[162:165], v[94:97]
	v_mfma_f32_16x16x32_bf16 v[30:33], v[138:141], v[162:165], v[30:33]
	v_mfma_f32_16x16x32_bf16 v[90:93], v[130:133], v[188:191], v[90:93]
	v_mfma_f32_16x16x32_bf16 v[26:29], v[138:141], v[188:191], v[26:29]
	v_mfma_f32_16x16x32_bf16 v[82:85], v[130:133], v[196:199], v[82:85]
	v_mfma_f32_16x16x32_bf16 v[18:21], v[138:141], v[196:199], v[18:21]
	v_mfma_f32_16x16x32_bf16 v[74:77], v[130:133], v[218:221], v[74:77]
	v_mfma_f32_16x16x32_bf16 v[10:13], v[138:141], v[218:221], v[10:13]
	v_mfma_f32_16x16x32_bf16 v[94:97], v[134:137], v[166:169], v[94:97]
	v_mfma_f32_16x16x32_bf16 v[30:33], v[142:145], v[166:169], v[30:33]
	v_mfma_f32_16x16x32_bf16 v[90:93], v[134:137], v[192:195], v[90:93]
	v_mfma_f32_16x16x32_bf16 v[26:29], v[142:145], v[192:195], v[26:29]
	v_mfma_f32_16x16x32_bf16 v[82:85], v[134:137], v[214:217], v[82:85]
	v_mfma_f32_16x16x32_bf16 v[18:21], v[142:145], v[214:217], v[18:21]
	v_mfma_f32_16x16x32_bf16 v[74:77], v[134:137], v[222:225], v[74:77]
	v_mfma_f32_16x16x32_bf16 v[10:13], v[142:145], v[222:225], v[10:13]
	v_mfma_f32_16x16x32_bf16 v[86:89], v[146:149], v[162:165], v[86:89]
	v_mfma_f32_16x16x32_bf16 v[22:25], v[154:157], v[162:165], v[22:25]
	v_mfma_f32_16x16x32_bf16 v[78:81], v[146:149], v[188:191], v[78:81]
	v_mfma_f32_16x16x32_bf16 v[14:17], v[154:157], v[188:191], v[14:17]
	v_mfma_f32_16x16x32_bf16 v[70:73], v[146:149], v[196:199], v[70:73]
	v_mfma_f32_16x16x32_bf16 v[6:9], v[154:157], v[196:199], v[6:9]
	v_mfma_f32_16x16x32_bf16 v[66:69], v[146:149], v[218:221], v[66:69]
	v_mfma_f32_16x16x32_bf16 v[2:5], v[154:157], v[218:221], v[2:5]
	v_mfma_f32_16x16x32_bf16 v[86:89], v[150:153], v[166:169], v[86:89]
	v_mfma_f32_16x16x32_bf16 v[22:25], v[158:161], v[166:169], v[22:25]
	v_mfma_f32_16x16x32_bf16 v[78:81], v[150:153], v[192:195], v[78:81]
	s_add_i32 s66, s66, 2
	v_mfma_f32_16x16x32_bf16 v[14:17], v[158:161], v[192:195], v[14:17]
	s_add_u32 vcc_lo, vcc_lo, 0x100
	v_mfma_f32_16x16x32_bf16 v[70:73], v[150:153], v[214:217], v[70:73]
	s_addc_u32 vcc_hi, vcc_hi, 0
	v_mfma_f32_16x16x32_bf16 v[6:9], v[158:161], v[214:217], v[6:9]
	s_mov_b64 s[88:89], s[90:91]
	v_mfma_f32_16x16x32_bf16 v[66:69], v[150:153], v[222:225], v[66:69]
	s_cmp_gt_u32 s66, 61
	v_mfma_f32_16x16x32_bf16 v[2:5], v[158:161], v[222:225], v[2:5]
	s_setprio 0
	s_barrier
	s_cbranch_scc0 .LBB0_651
	s_and_b64 vcc, exec, s[36:37]
	s_cbranch_vccz .LBB0_654
	s_barrier

.LBB0_824:
	s_and_b32 s50, s4, 3
	s_lshl_b32 s4, s5, 13
	s_lshl_b32 s7, s50, 12
	s_add_u32 s18, s42, 0x80000
	s_addc_u32 s19, s43, 0
	s_add_i32 m0, s1, 0x18000
	v_lshl_add_u64 v[10:11], s[18:19], 0, v[132:133]
	s_waitcnt vmcnt(2)
	s_barrier
	global_load_lds_dwordx4 v[10:11], off
	s_add_i32 m0, s1, 0x1a000
	v_lshl_add_u64 v[10:11], s[18:19], 0, v[136:137]
	s_add_u32 s18, s44, 0x200000
	s_addc_u32 s19, s45, 0
	s_add_i32 s51, s1, 0x8000
	global_load_lds_dwordx4 v[10:11], off
	v_lshl_add_u64 v[10:11], s[18:19], 0, v[130:131]
	s_mov_b32 m0, s51
	s_add_i32 s52, s1, 0xa000
	global_load_lds_dwordx4 v[10:11], off
	v_lshl_add_u64 v[10:11], s[18:19], 0, v[134:135]
	s_add_u32 s18, s42, 0x84000
	s_mov_b32 m0, s52
	s_addc_u32 s19, s43, 0
	global_load_lds_dwordx4 v[10:11], off
	s_add_i32 m0, s1, 0x1c000
	v_lshl_add_u64 v[10:11], s[18:19], 0, v[132:133]
	global_load_lds_dwordx4 v[10:11], off
	v_lshl_add_u64 v[10:11], s[18:19], 0, v[136:137]
	s_add_i32 m0, s1, 0x1e000
	v_bfe_u32 v9, v2, 4, 2
	global_load_lds_dwordx4 v[10:11], off
	v_and_b32_e32 v10, 15, v2
	v_lshlrev_b32_e32 v12, 4, v9
	v_lshlrev_b32_e32 v2, 2, v2
	v_lshl_or_b32 v1, s5, 6, v10
	v_lshl_or_b32 v10, v10, 6, v12
	v_and_b32_e32 v2, 32, v2
	v_bitop3_b32 v12, v10, s4, v2 bitop3:0xde
	v_bitop3_b32 v150, v10, s7, v2 bitop3:0xde
	v_lshlrev_b32_e32 v2, 10, v3
	v_and_b32_e32 v2, 0xfffff800, v2
	v_lshl_add_u32 v2, v4, 7, v2
	v_and_b32_e32 v3, 1, v3
	v_lshl_or_b32 v2, v3, 6, v2
	v_lshl_add_u32 v138, v5, 1, v2
	v_lshlrev_b32_e32 v2, 10, v6
	v_and_b32_e32 v2, 0xfffff800, v2
	s_waitcnt vmcnt(6)
	s_cmpk_lt_u32 s6, 0x100
	v_lshl_add_u32 v2, v7, 7, v2
	v_and_b32_e32 v3, 1, v6
	v_lshlrev_b32_e32 v11, 3, v9
	s_cselect_b64 s[18:19], -1, 0
	v_lshl_or_b32 v2, v3, 6, v2
	s_add_i32 s55, 0, 0x10000
	s_add_i32 s56, 0, 0x14000
	v_lshl_or_b32 v151, s50, 5, v11
	v_cmp_eq_u32_e64 s[6:7], 0, v9
	s_ashr_i32 s53, s97, 31
	s_ashr_i32 s54, s2, 31
	v_mov_b32_e32 v139, v133
	v_lshl_add_u32 v140, v8, 1, v2
	v_mov_b32_e32 v141, v133
	v_mov_b64_e32 v[142:143], 0x400
	v_mov_b64_e32 v[144:145], 0x3ff
	v_add_u32_e32 v152, s55, v150
	v_add_u32_e32 v153, s56, v150
	v_add_u32_e32 v154, 0, v12
	s_mov_b32 s57, 0
	v_add_u32_e32 v226, 0x18000, v150
	v_add_u32_e32 v227, 0x1c000, v150
	s_barrier
	s_branch .LBB0_827

.LBB0_834:
	ds_read_b128 v[146:149], v152
	ds_read_b128 v[156:159], v152 offset:1024
	ds_read_b128 v[160:163], v152 offset:2048
	ds_read_b128 v[164:167], v152 offset:3072
	ds_read_b128 v[168:171], v153
	ds_read_b128 v[172:175], v153 offset:1024
	ds_read_b128 v[176:179], v153 offset:2048
	ds_read_b128 v[180:183], v153 offset:3072
	ds_read_b128 v[184:187], v154
	ds_read_b128 v[188:191], v154 offset:1024
	ds_read_b128 v[192:195], v154 offset:2048
	ds_read_b128 v[196:199], v154 offset:3072
	ds_read_b128 v[206:209], v154 offset:4096
	ds_read_b128 v[210:213], v154 offset:5120
	s_add_i32 m0, s1, 0xc000
	ds_read_b128 v[214:217], v154 offset:6144
	global_load_lds_dwordx4 v138, s[42:43]
	s_add_i32 m0, s1, 0xe000
	ds_read_b128 v[218:221], v154 offset:7168
	global_load_lds_dwordx4 v140, s[42:43]
	s_waitcnt vmcnt(8) lgkmcnt(0)
	s_barrier
	s_setprio 1
	v_mfma_f32_16x16x32_bf16 v[126:129], v[146:149], v[184:187], v[126:129]
	v_mfma_f32_16x16x32_bf16 v[122:125], v[160:163], v[184:187], v[122:125]
	v_mfma_f32_16x16x32_bf16 v[110:113], v[146:149], v[192:195], v[110:113]
	s_add_u32 s34, s42, 0x1fc000
	v_mfma_f32_16x16x32_bf16 v[106:109], v[160:163], v[192:195], v[106:109]
	s_addc_u32 s44, s43, 0
	v_mfma_f32_16x16x32_bf16 v[94:97], v[146:149], v[206:209], v[94:97]
	s_cmpk_eq_i32 s61, 0xa8
	v_mfma_f32_16x16x32_bf16 v[90:93], v[160:163], v[206:209], v[90:93]
	s_cselect_b32 s48, s41, s34
	v_mfma_f32_16x16x32_bf16 v[78:81], v[146:149], v[214:217], v[78:81]
	s_cselect_b32 s49, s23, s44
	v_mfma_f32_16x16x32_bf16 v[74:77], v[160:163], v[214:217], v[74:77]
	s_cselect_b32 s47, s21, s60
	v_mfma_f32_16x16x32_bf16 v[126:129], v[156:159], v[188:191], v[126:129]
	s_cselect_b32 s46, s58, s59
	v_mfma_f32_16x16x32_bf16 v[122:125], v[164:167], v[188:191], v[122:125]
	s_add_u32 s44, s48, 0x200000
	v_mfma_f32_16x16x32_bf16 v[110:113], v[156:159], v[196:199], v[110:113]
	s_addc_u32 s45, s49, 0
	v_mfma_f32_16x16x32_bf16 v[106:109], v[164:167], v[196:199], v[106:109]
	s_add_u32 s62, s46, 0x4000
	v_mfma_f32_16x16x32_bf16 v[94:97], v[156:159], v[210:213], v[94:97]
	s_addc_u32 s63, s47, 0
	v_mfma_f32_16x16x32_bf16 v[90:93], v[164:167], v[210:213], v[90:93]
	s_add_u32 s100, s48, 0x4000
	v_mfma_f32_16x16x32_bf16 v[78:81], v[156:159], v[218:221], v[78:81]
	s_addc_u32 s101, s49, 0
	v_mfma_f32_16x16x32_bf16 v[74:77], v[164:167], v[218:221], v[74:77]
	s_add_u32 s98, s46, 0x80000
	v_mfma_f32_16x16x32_bf16 v[118:121], v[168:171], v[184:187], v[118:121]
	s_addc_u32 s99, s47, 0
	v_mfma_f32_16x16x32_bf16 v[114:117], v[176:179], v[184:187], v[114:117]
	s_add_u32 s24, s46, 0x84000
	v_mfma_f32_16x16x32_bf16 v[102:105], v[168:171], v[192:195], v[102:105]
	s_addc_u32 s25, s47, 0
	v_mfma_f32_16x16x32_bf16 v[98:101], v[176:179], v[192:195], v[98:101]
	v_mfma_f32_16x16x32_bf16 v[86:89], v[168:171], v[206:209], v[86:89]
	v_mfma_f32_16x16x32_bf16 v[82:85], v[176:179], v[206:209], v[82:85]
	v_mfma_f32_16x16x32_bf16 v[70:73], v[168:171], v[214:217], v[70:73]
	v_mfma_f32_16x16x32_bf16 v[66:69], v[176:179], v[214:217], v[66:69]
	v_mfma_f32_16x16x32_bf16 v[118:121], v[172:175], v[188:191], v[118:121]
	v_mfma_f32_16x16x32_bf16 v[114:117], v[180:183], v[188:191], v[114:117]
	v_mfma_f32_16x16x32_bf16 v[102:105], v[172:175], v[196:199], v[102:105]
	v_mfma_f32_16x16x32_bf16 v[98:101], v[180:183], v[196:199], v[98:101]
	v_mfma_f32_16x16x32_bf16 v[86:89], v[172:175], v[210:213], v[86:89]
	v_mfma_f32_16x16x32_bf16 v[82:85], v[180:183], v[210:213], v[82:85]
	v_mfma_f32_16x16x32_bf16 v[70:73], v[172:175], v[218:221], v[70:73]
	v_mfma_f32_16x16x32_bf16 v[66:69], v[180:183], v[218:221], v[66:69]
	s_setprio 0
	s_barrier
	ds_read_b128 v[184:187], v154 offset:16384
	ds_read_b128 v[188:191], v154 offset:17408
	s_add_i32 m0, s1, 0x10000
	ds_read_b128 v[192:195], v154 offset:18432
	global_load_lds_dwordx4 v132, s[46:47]
	s_add_i32 m0, s1, 0x12000
	ds_read_b128 v[196:199], v154 offset:19456
	global_load_lds_dwordx4 v136, s[46:47]
	s_add_i32 m0, s1, 0x14000
	ds_read_b128 v[206:209], v154 offset:20480
	global_load_lds_dwordx4 v132, s[62:63]
	s_add_i32 m0, s1, 0x16000
	ds_read_b128 v[210:213], v154 offset:21504
	global_load_lds_dwordx4 v136, s[62:63]
	s_mov_b32 m0, s1
	ds_read_b128 v[214:217], v154 offset:22528
	global_load_lds_dwordx4 v130, s[48:49]
	s_add_i32 m0, s1, 0x2000
	ds_read_b128 v[218:221], v154 offset:23552
	global_load_lds_dwordx4 v134, s[48:49]
	s_waitcnt vmcnt(8) lgkmcnt(0)
	s_barrier
	s_setprio 1
	v_mfma_f32_16x16x32_bf16 v[62:65], v[146:149], v[184:187], v[62:65]
	v_mfma_f32_16x16x32_bf16 v[58:61], v[160:163], v[184:187], v[58:61]
	v_mfma_f32_16x16x32_bf16 v[46:49], v[146:149], v[192:195], v[46:49]
	v_mfma_f32_16x16x32_bf16 v[42:45], v[160:163], v[192:195], v[42:45]
	v_mfma_f32_16x16x32_bf16 v[30:33], v[146:149], v[206:209], v[30:33]
	v_mfma_f32_16x16x32_bf16 v[26:29], v[160:163], v[206:209], v[26:29]
	v_mfma_f32_16x16x32_bf16 v[14:17], v[146:149], v[214:217], v[14:17]
	v_mfma_f32_16x16x32_bf16 v[10:13], v[160:163], v[214:217], v[10:13]
	v_mfma_f32_16x16x32_bf16 v[62:65], v[156:159], v[188:191], v[62:65]
	v_mfma_f32_16x16x32_bf16 v[58:61], v[164:167], v[188:191], v[58:61]
	v_mfma_f32_16x16x32_bf16 v[46:49], v[156:159], v[196:199], v[46:49]
	v_mfma_f32_16x16x32_bf16 v[42:45], v[164:167], v[196:199], v[42:45]
	v_mfma_f32_16x16x32_bf16 v[30:33], v[156:159], v[210:213], v[30:33]
	v_mfma_f32_16x16x32_bf16 v[26:29], v[164:167], v[210:213], v[26:29]
	v_mfma_f32_16x16x32_bf16 v[14:17], v[156:159], v[218:221], v[14:17]
	v_mfma_f32_16x16x32_bf16 v[10:13], v[164:167], v[218:221], v[10:13]
	v_mfma_f32_16x16x32_bf16 v[54:57], v[168:171], v[184:187], v[54:57]
	v_mfma_f32_16x16x32_bf16 v[50:53], v[176:179], v[184:187], v[50:53]
	v_mfma_f32_16x16x32_bf16 v[38:41], v[168:171], v[192:195], v[38:41]
	v_mfma_f32_16x16x32_bf16 v[34:37], v[176:179], v[192:195], v[34:37]
	v_mfma_f32_16x16x32_bf16 v[22:25], v[168:171], v[206:209], v[22:25]
	v_mfma_f32_16x16x32_bf16 v[18:21], v[176:179], v[206:209], v[18:21]
	v_mfma_f32_16x16x32_bf16 v[6:9], v[168:171], v[214:217], v[6:9]
	v_mfma_f32_16x16x32_bf16 v[2:5], v[176:179], v[214:217], v[2:5]
	v_mfma_f32_16x16x32_bf16 v[54:57], v[172:175], v[188:191], v[54:57]
	v_mfma_f32_16x16x32_bf16 v[50:53], v[180:183], v[188:191], v[50:53]
	v_mfma_f32_16x16x32_bf16 v[38:41], v[172:175], v[196:199], v[38:41]
	v_mfma_f32_16x16x32_bf16 v[34:37], v[180:183], v[196:199], v[34:37]
	v_mfma_f32_16x16x32_bf16 v[22:25], v[172:175], v[210:213], v[22:25]
	v_mfma_f32_16x16x32_bf16 v[18:21], v[180:183], v[210:213], v[18:21]
	v_mfma_f32_16x16x32_bf16 v[6:9], v[172:175], v[218:221], v[6:9]
	v_mfma_f32_16x16x32_bf16 v[2:5], v[180:183], v[218:221], v[2:5]
	s_setprio 0
	s_barrier
	ds_read_b128 v[146:149], v226
	ds_read_b128 v[156:159], v226 offset:1024
	ds_read_b128 v[160:163], v226 offset:2048
	ds_read_b128 v[164:167], v226 offset:3072
	ds_read_b128 v[168:171], v227
	ds_read_b128 v[172:175], v227 offset:1024
	ds_read_b128 v[176:179], v227 offset:2048
	ds_read_b128 v[180:183], v227 offset:3072
	ds_read_b128 v[184:187], v154 offset:32768
	ds_read_b128 v[188:191], v154 offset:33792
	ds_read_b128 v[192:195], v154 offset:34816
	ds_read_b128 v[196:199], v154 offset:35840
	ds_read_b128 v[206:209], v154 offset:36864
	ds_read_b128 v[210:213], v154 offset:37888
	s_add_i32 m0, s1, 0x4000
	ds_read_b128 v[214:217], v154 offset:38912
	global_load_lds_dwordx4 v130, s[100:101]
	s_add_i32 m0, s1, 0x6000
	ds_read_b128 v[218:221], v154 offset:39936
	global_load_lds_dwordx4 v134, s[100:101]
	s_waitcnt vmcnt(8) lgkmcnt(0)
	s_barrier
	s_setprio 1
	v_mfma_f32_16x16x32_bf16 v[126:129], v[146:149], v[184:187], v[126:129]
	v_mfma_f32_16x16x32_bf16 v[122:125], v[160:163], v[184:187], v[122:125]
	v_mfma_f32_16x16x32_bf16 v[110:113], v[146:149], v[192:195], v[110:113]
	v_mfma_f32_16x16x32_bf16 v[106:109], v[160:163], v[192:195], v[106:109]
	v_mfma_f32_16x16x32_bf16 v[94:97], v[146:149], v[206:209], v[94:97]
	v_mfma_f32_16x16x32_bf16 v[90:93], v[160:163], v[206:209], v[90:93]
	v_mfma_f32_16x16x32_bf16 v[78:81], v[146:149], v[214:217], v[78:81]
	v_mfma_f32_16x16x32_bf16 v[74:77], v[160:163], v[214:217], v[74:77]
	v_mfma_f32_16x16x32_bf16 v[126:129], v[156:159], v[188:191], v[126:129]
	v_mfma_f32_16x16x32_bf16 v[122:125], v[164:167], v[188:191], v[122:125]
	v_mfma_f32_16x16x32_bf16 v[110:113], v[156:159], v[196:199], v[110:113]
	v_mfma_f32_16x16x32_bf16 v[106:109], v[164:167], v[196:199], v[106:109]
	v_mfma_f32_16x16x32_bf16 v[94:97], v[156:159], v[210:213], v[94:97]
	v_mfma_f32_16x16x32_bf16 v[90:93], v[164:167], v[210:213], v[90:93]
	v_mfma_f32_16x16x32_bf16 v[78:81], v[156:159], v[218:221], v[78:81]
	v_mfma_f32_16x16x32_bf16 v[74:77], v[164:167], v[218:221], v[74:77]
	v_mfma_f32_16x16x32_bf16 v[118:121], v[168:171], v[184:187], v[118:121]
	v_mfma_f32_16x16x32_bf16 v[114:117], v[176:179], v[184:187], v[114:117]
	v_mfma_f32_16x16x32_bf16 v[102:105], v[168:171], v[192:195], v[102:105]
	v_mfma_f32_16x16x32_bf16 v[98:101], v[176:179], v[192:195], v[98:101]
	v_mfma_f32_16x16x32_bf16 v[86:89], v[168:171], v[206:209], v[86:89]
	v_mfma_f32_16x16x32_bf16 v[82:85], v[176:179], v[206:209], v[82:85]
	v_mfma_f32_16x16x32_bf16 v[70:73], v[168:171], v[214:217], v[70:73]
	v_mfma_f32_16x16x32_bf16 v[66:69], v[176:179], v[214:217], v[66:69]
	v_mfma_f32_16x16x32_bf16 v[118:121], v[172:175], v[188:191], v[118:121]
	v_mfma_f32_16x16x32_bf16 v[114:117], v[180:183], v[188:191], v[114:117]
	v_mfma_f32_16x16x32_bf16 v[102:105], v[172:175], v[196:199], v[102:105]
	v_mfma_f32_16x16x32_bf16 v[98:101], v[180:183], v[196:199], v[98:101]
	v_mfma_f32_16x16x32_bf16 v[86:89], v[172:175], v[210:213], v[86:89]
	v_mfma_f32_16x16x32_bf16 v[82:85], v[180:183], v[210:213], v[82:85]
	v_mfma_f32_16x16x32_bf16 v[70:73], v[172:175], v[218:221], v[70:73]
	v_mfma_f32_16x16x32_bf16 v[66:69], v[180:183], v[218:221], v[66:69]
	s_setprio 0
	s_barrier
	ds_read_b128 v[184:187], v154 offset:49152
	ds_read_b128 v[188:191], v154 offset:50176
	s_add_i32 m0, s1, 0x18000
	ds_read_b128 v[192:195], v154 offset:51200
	global_load_lds_dwordx4 v132, s[98:99]
	s_add_i32 m0, s1, 0x1a000
	ds_read_b128 v[196:199], v154 offset:52224
	global_load_lds_dwordx4 v136, s[98:99]
	s_add_i32 m0, s1, 0x1c000
	ds_read_b128 v[206:209], v154 offset:53248
	global_load_lds_dwordx4 v132, s[24:25]
	s_add_i32 m0, s1, 0x1e000
	ds_read_b128 v[210:213], v154 offset:54272
	global_load_lds_dwordx4 v136, s[24:25]
	s_add_i32 m0, s1, 0x8000
	ds_read_b128 v[214:217], v154 offset:55296
	global_load_lds_dwordx4 v130, s[44:45]
	s_add_i32 m0, s1, 0xa000
	ds_read_b128 v[218:221], v154 offset:56320
	global_load_lds_dwordx4 v134, s[44:45]
	s_waitcnt vmcnt(8) lgkmcnt(0)
	s_barrier
	s_setprio 1
	v_mfma_f32_16x16x32_bf16 v[62:65], v[146:149], v[184:187], v[62:65]
	v_mfma_f32_16x16x32_bf16 v[58:61], v[160:163], v[184:187], v[58:61]
	v_mfma_f32_16x16x32_bf16 v[46:49], v[146:149], v[192:195], v[46:49]
	v_mfma_f32_16x16x32_bf16 v[42:45], v[160:163], v[192:195], v[42:45]
	v_mfma_f32_16x16x32_bf16 v[30:33], v[146:149], v[206:209], v[30:33]
	v_mfma_f32_16x16x32_bf16 v[26:29], v[160:163], v[206:209], v[26:29]
	v_mfma_f32_16x16x32_bf16 v[14:17], v[146:149], v[214:217], v[14:17]
	v_mfma_f32_16x16x32_bf16 v[10:13], v[160:163], v[214:217], v[10:13]
	v_mfma_f32_16x16x32_bf16 v[62:65], v[156:159], v[188:191], v[62:65]
	v_mfma_f32_16x16x32_bf16 v[58:61], v[164:167], v[188:191], v[58:61]
	v_mfma_f32_16x16x32_bf16 v[46:49], v[156:159], v[196:199], v[46:49]
	v_mfma_f32_16x16x32_bf16 v[42:45], v[164:167], v[196:199], v[42:45]
	v_mfma_f32_16x16x32_bf16 v[30:33], v[156:159], v[210:213], v[30:33]
	v_mfma_f32_16x16x32_bf16 v[26:29], v[164:167], v[210:213], v[26:29]
	v_mfma_f32_16x16x32_bf16 v[14:17], v[156:159], v[218:221], v[14:17]
	v_mfma_f32_16x16x32_bf16 v[10:13], v[164:167], v[218:221], v[10:13]
	v_mfma_f32_16x16x32_bf16 v[54:57], v[168:171], v[184:187], v[54:57]
	v_mfma_f32_16x16x32_bf16 v[50:53], v[176:179], v[184:187], v[50:53]
	v_mfma_f32_16x16x32_bf16 v[38:41], v[168:171], v[192:195], v[38:41]
	v_mfma_f32_16x16x32_bf16 v[34:37], v[176:179], v[192:195], v[34:37]
	v_mfma_f32_16x16x32_bf16 v[22:25], v[168:171], v[206:209], v[22:25]
	v_mfma_f32_16x16x32_bf16 v[18:21], v[176:179], v[206:209], v[18:21]
	v_mfma_f32_16x16x32_bf16 v[6:9], v[168:171], v[214:217], v[6:9]
	v_mfma_f32_16x16x32_bf16 v[2:5], v[176:179], v[214:217], v[2:5]
	v_mfma_f32_16x16x32_bf16 v[54:57], v[172:175], v[188:191], v[54:57]
	v_mfma_f32_16x16x32_bf16 v[50:53], v[180:183], v[188:191], v[50:53]
	s_add_i32 s61, s61, 2
	v_mfma_f32_16x16x32_bf16 v[38:41], v[172:175], v[196:199], v[38:41]
	s_add_u32 s59, s59, 0x100000
	v_mfma_f32_16x16x32_bf16 v[34:37], v[180:183], v[196:199], v[34:37]
	s_addc_u32 s60, s60, 0
	v_mfma_f32_16x16x32_bf16 v[22:25], v[172:175], v[210:213], v[22:25]
	s_add_u32 s42, s42, 0x400000
	v_mfma_f32_16x16x32_bf16 v[18:21], v[180:183], v[210:213], v[18:21]
	s_addc_u32 s43, s43, 0
	v_mfma_f32_16x16x32_bf16 v[6:9], v[172:175], v[218:221], v[6:9]
	s_cmpk_gt_u32 s61, 0xa9
	v_mfma_f32_16x16x32_bf16 v[2:5], v[180:183], v[218:221], v[2:5]
	s_setprio 0
	s_barrier
	s_cbranch_scc0 .LBB0_834
	s_and_b64 vcc, exec, s[18:19]
	s_cbranch_vccz .LBB0_837
	s_barrier
